# 7 GEMM inner-loop heads aligned to 64 bytes with .p2align (on top of v8)
# speedup vs baseline: 1.0048x; 1.0048x over previous
; template <class Epi, bool ALIGN_EPI>
; __device__ __forceinline__ void gemm_phase(LAS unsigned char* lds, const Gemm g, const StaticOrder& S, const Epi& E) {
;     ...
;         const bool has_next = S.next(ui + 1, nxt);
;         const char* nA = has_next ? (const char*)g.A + (size_t)nxt.pm * tstepA : cA; const char* nB = has_next ? (const char*)g.Bt + (size_t)nxt.pn * tstepB : cB;
;         for (int t = 0; t < nt; t += 2) {
;             const bool last = (t == nt - 2);
;             const char* a1 = cA + (size_t)(t + 1) * kstep;
;             const char* a2 = last ? nA : cA + (size_t)(t + 2) * kstep; const char* b2 = last ? nB : cB + (size_t)(t + 2) * kstep;
;     ...
; #pragma unroll
;         for (int a = 0; a < 2; ++a)
; #pragma unroll
;             for (int b = 0; b < 2; ++b)
; #pragma unroll
;                 for (int m = 0; m < 4; ++m)
; #pragma unroll
;                     for (int n = 0; n < 2; ++n) acc[a][b][m][n] = (f32x4){0.f, 0.f, 0.f, 0.f};
;         cur = nxt; cA = nA; cB = nB; ++ui;
.LBB0_120:
	s_ashr_i32 s17, s16, 31
	s_lshl_b64 s[18:19], s[16:17], 20
	s_add_u32 s18, s30, s18
	s_addc_u32 s19, s31, s19
	s_and_b64 s[20:21], s[0:1], exec
	s_cselect_b32 s17, s19, s27
	s_cselect_b32 s51, s18, s26
	s_ashr_i32 s15, s14, 31
	s_lshl_b64 s[20:21], s[14:15], 20
	s_add_u32 s20, s33, s20
	s_addc_u32 s21, s34, s21
	s_and_b64 s[28:29], s[0:1], exec
	s_cselect_b32 s15, s21, s25
	s_cselect_b32 s52, s20, s24
	s_add_u32 s53, s24, 0x100
	s_addc_u32 s54, s25, 0
	s_add_u32 s24, s26, 0x80080
	v_mov_b32_e32 v0, 0
	s_addc_u32 s25, s27, 0
	s_mov_b32 s55, -2
	v_mov_b32_e32 v1, v0
	v_mov_b32_e32 v2, v0
	v_mov_b32_e32 v3, v0
	v_mov_b32_e32 v4, v0
	v_mov_b32_e32 v5, v0
	v_mov_b32_e32 v6, v0
	v_mov_b32_e32 v7, v0
	v_mov_b32_e32 v16, v0
	v_mov_b32_e32 v17, v0
	v_mov_b32_e32 v18, v0
	v_mov_b32_e32 v19, v0
	v_mov_b32_e32 v20, v0
	v_mov_b32_e32 v21, v0
	v_mov_b32_e32 v22, v0
	v_mov_b32_e32 v23, v0
	v_mov_b32_e32 v32, v0
	v_mov_b32_e32 v33, v0
	v_mov_b32_e32 v34, v0
	v_mov_b32_e32 v35, v0
	v_mov_b32_e32 v36, v0
	v_mov_b32_e32 v37, v0
	v_mov_b32_e32 v38, v0
	v_mov_b32_e32 v39, v0
	v_mov_b32_e32 v48, v0
	v_mov_b32_e32 v49, v0
	v_mov_b32_e32 v50, v0
	v_mov_b32_e32 v51, v0
	v_mov_b32_e32 v52, v0
	v_mov_b32_e32 v53, v0
	v_mov_b32_e32 v54, v0
	v_mov_b32_e32 v55, v0
	v_mov_b32_e32 v8, v0
	v_mov_b32_e32 v9, v0
	v_mov_b32_e32 v10, v0
	v_mov_b32_e32 v11, v0
	v_mov_b32_e32 v12, v0
	v_mov_b32_e32 v13, v0
	v_mov_b32_e32 v14, v0
	v_mov_b32_e32 v15, v0
	v_mov_b32_e32 v24, v0
	v_mov_b32_e32 v25, v0
	v_mov_b32_e32 v26, v0
	v_mov_b32_e32 v27, v0
	v_mov_b32_e32 v28, v0
	v_mov_b32_e32 v29, v0
	v_mov_b32_e32 v30, v0
	v_mov_b32_e32 v31, v0
	v_mov_b32_e32 v40, v0
	v_mov_b32_e32 v41, v0
	v_mov_b32_e32 v42, v0
	v_mov_b32_e32 v43, v0
	v_mov_b32_e32 v44, v0
	v_mov_b32_e32 v45, v0
	v_mov_b32_e32 v46, v0
	v_mov_b32_e32 v47, v0
	v_mov_b32_e32 v56, v0
	v_mov_b32_e32 v57, v0
	v_mov_b32_e32 v58, v0
	v_mov_b32_e32 v59, v0
	v_mov_b32_e32 v60, v0
	v_mov_b32_e32 v61, v0
	v_mov_b32_e32 v62, v0
	v_mov_b32_e32 v63, v0
	v_mov_b32_e32 v64, v0
	v_mov_b32_e32 v65, v0
	v_mov_b32_e32 v66, v0
	v_mov_b32_e32 v67, v0
	v_mov_b32_e32 v68, v0
	v_mov_b32_e32 v69, v0
	v_mov_b32_e32 v70, v0
	v_mov_b32_e32 v71, v0
	v_mov_b32_e32 v80, v0
	v_mov_b32_e32 v81, v0
	v_mov_b32_e32 v82, v0
	v_mov_b32_e32 v83, v0
	v_mov_b32_e32 v84, v0
	v_mov_b32_e32 v85, v0
	v_mov_b32_e32 v86, v0
	v_mov_b32_e32 v87, v0
	v_mov_b32_e32 v96, v0
	v_mov_b32_e32 v97, v0
	v_mov_b32_e32 v98, v0
	v_mov_b32_e32 v99, v0
	v_mov_b32_e32 v100, v0
	v_mov_b32_e32 v101, v0
	v_mov_b32_e32 v102, v0
	v_mov_b32_e32 v103, v0
	v_mov_b32_e32 v112, v0
	v_mov_b32_e32 v113, v0
	v_mov_b32_e32 v114, v0
	v_mov_b32_e32 v115, v0
	v_mov_b32_e32 v116, v0
	v_mov_b32_e32 v117, v0
	v_mov_b32_e32 v118, v0
	v_mov_b32_e32 v119, v0
	v_mov_b32_e32 v72, v0
	v_mov_b32_e32 v73, v0
	v_mov_b32_e32 v74, v0
	v_mov_b32_e32 v75, v0
	v_mov_b32_e32 v76, v0
	v_mov_b32_e32 v77, v0
	v_mov_b32_e32 v78, v0
	v_mov_b32_e32 v79, v0
	v_mov_b32_e32 v88, v0
	v_mov_b32_e32 v89, v0
	v_mov_b32_e32 v90, v0
	v_mov_b32_e32 v91, v0
	v_mov_b32_e32 v92, v0
	v_mov_b32_e32 v93, v0
	v_mov_b32_e32 v94, v0
	v_mov_b32_e32 v95, v0
	v_mov_b32_e32 v104, v0
	v_mov_b32_e32 v105, v0
	v_mov_b32_e32 v106, v0
	v_mov_b32_e32 v107, v0
	v_mov_b32_e32 v108, v0
	v_mov_b32_e32 v109, v0
	v_mov_b32_e32 v110, v0
	v_mov_b32_e32 v111, v0
	v_mov_b32_e32 v120, v0
	v_mov_b32_e32 v121, v0
	v_mov_b32_e32 v122, v0
	v_mov_b32_e32 v123, v0
	v_mov_b32_e32 v124, v0
	v_mov_b32_e32 v125, v0
	v_mov_b32_e32 v126, v0
	v_mov_b32_e32 v127, v0
	.p2align	6

; template <class Epi, bool ALIGN_EPI>
; __device__ __forceinline__ void gemm_phase(LAS unsigned char* lds, const Gemm g, const StaticOrder& S, const Epi& E) {
;     ...
; #pragma unroll
;         for (int a = 0; a < 2; ++a)
; #pragma unroll
;             for (int b = 0; b < 2; ++b)
; #pragma unroll
;                 for (int m = 0; m < 4; ++m)
; #pragma unroll
;                     for (int n = 0; n < 2; ++n) acc[a][b][m][n] = (f32x4){0.f, 0.f, 0.f, 0.f};
;         cur = nxt; cA = nA; cB = nB; ++ui;
.LBB0_308:
	s_add_u32 s63, s34, 0x100
	v_mov_b32_e32 v0, 0
	s_addc_u32 s64, s35, 0
	s_mov_b32 s65, -2
	s_waitcnt lgkmcnt(0)
	v_mov_b32_e32 v1, v0
	v_mov_b32_e32 v2, v0
	v_mov_b32_e32 v3, v0
	v_mov_b32_e32 v4, v0
	v_mov_b32_e32 v5, v0
	v_mov_b32_e32 v6, v0
	v_mov_b32_e32 v7, v0
	v_mov_b32_e32 v16, v0
	v_mov_b32_e32 v17, v0
	v_mov_b32_e32 v18, v0
	v_mov_b32_e32 v19, v0
	v_mov_b32_e32 v20, v0
	v_mov_b32_e32 v21, v0
	v_mov_b32_e32 v22, v0
	v_mov_b32_e32 v23, v0
	v_mov_b32_e32 v32, v0
	v_mov_b32_e32 v33, v0
	v_mov_b32_e32 v34, v0
	v_mov_b32_e32 v35, v0
	v_mov_b32_e32 v36, v0
	v_mov_b32_e32 v37, v0
	v_mov_b32_e32 v38, v0
	v_mov_b32_e32 v39, v0
	v_mov_b32_e32 v48, v0
	v_mov_b32_e32 v49, v0
	v_mov_b32_e32 v50, v0
	v_mov_b32_e32 v51, v0
	v_mov_b32_e32 v52, v0
	v_mov_b32_e32 v53, v0
	v_mov_b32_e32 v54, v0
	v_mov_b32_e32 v55, v0
	v_mov_b32_e32 v8, v0
	v_mov_b32_e32 v9, v0
	v_mov_b32_e32 v10, v0
	v_mov_b32_e32 v11, v0
	v_mov_b32_e32 v12, v0
	v_mov_b32_e32 v13, v0
	v_mov_b32_e32 v14, v0
	v_mov_b32_e32 v15, v0
	v_mov_b32_e32 v24, v0
	v_mov_b32_e32 v25, v0
	v_mov_b32_e32 v26, v0
	v_mov_b32_e32 v27, v0
	v_mov_b32_e32 v28, v0
	v_mov_b32_e32 v29, v0
	v_mov_b32_e32 v30, v0
	v_mov_b32_e32 v31, v0
	v_mov_b32_e32 v40, v0
	v_mov_b32_e32 v41, v0
	v_mov_b32_e32 v42, v0
	v_mov_b32_e32 v43, v0
	v_mov_b32_e32 v44, v0
	v_mov_b32_e32 v45, v0
	v_mov_b32_e32 v46, v0
	v_mov_b32_e32 v47, v0
	v_mov_b32_e32 v56, v0
	v_mov_b32_e32 v57, v0
	v_mov_b32_e32 v58, v0
	v_mov_b32_e32 v59, v0
	v_mov_b32_e32 v60, v0
	v_mov_b32_e32 v61, v0
	v_mov_b32_e32 v62, v0
	v_mov_b32_e32 v63, v0
	v_mov_b32_e32 v68, v0
	v_mov_b32_e32 v69, v0
	v_mov_b32_e32 v70, v0
	v_mov_b32_e32 v71, v0
	v_mov_b32_e32 v76, v0
	v_mov_b32_e32 v77, v0
	v_mov_b32_e32 v78, v0
	v_mov_b32_e32 v79, v0
	v_mov_b32_e32 v96, v0
	v_mov_b32_e32 v97, v0
	v_mov_b32_e32 v98, v0
	v_mov_b32_e32 v99, v0
	v_mov_b32_e32 v100, v0
	v_mov_b32_e32 v101, v0
	v_mov_b32_e32 v102, v0
	v_mov_b32_e32 v103, v0
	v_mov_b32_e32 v112, v0
	v_mov_b32_e32 v113, v0
	v_mov_b32_e32 v114, v0
	v_mov_b32_e32 v115, v0
	v_mov_b32_e32 v116, v0
	v_mov_b32_e32 v117, v0
	v_mov_b32_e32 v118, v0
	v_mov_b32_e32 v119, v0
	v_mov_b32_e32 v128, v0
	v_mov_b32_e32 v129, v0
	v_mov_b32_e32 v130, v0
	v_mov_b32_e32 v131, v0
	v_mov_b32_e32 v132, v0
	v_mov_b32_e32 v133, v0
	v_mov_b32_e32 v134, v0
	v_mov_b32_e32 v135, v0
	v_mov_b32_e32 v88, v0
	v_mov_b32_e32 v89, v0
	v_mov_b32_e32 v90, v0
	v_mov_b32_e32 v91, v0
	v_mov_b32_e32 v92, v0
	v_mov_b32_e32 v93, v0
	v_mov_b32_e32 v94, v0
	v_mov_b32_e32 v95, v0
	v_mov_b32_e32 v104, v0
	v_mov_b32_e32 v105, v0
	v_mov_b32_e32 v106, v0
	v_mov_b32_e32 v107, v0
	v_mov_b32_e32 v108, v0
	v_mov_b32_e32 v109, v0
	v_mov_b32_e32 v110, v0
	v_mov_b32_e32 v111, v0
	v_mov_b32_e32 v120, v0
	v_mov_b32_e32 v121, v0
	v_mov_b32_e32 v122, v0
	v_mov_b32_e32 v123, v0
	v_mov_b32_e32 v124, v0
	v_mov_b32_e32 v125, v0
	v_mov_b32_e32 v126, v0
	v_mov_b32_e32 v127, v0
	v_mov_b32_e32 v136, v0
	v_mov_b32_e32 v137, v0
	v_mov_b32_e32 v138, v0
	v_mov_b32_e32 v139, v0
	v_mov_b32_e32 v140, v0
	v_mov_b32_e32 v141, v0
	v_mov_b32_e32 v142, v0
	v_mov_b32_e32 v143, v0
	.p2align	6

; template <class Epi, bool ALIGN_EPI>
; __device__ __forceinline__ void gemm_phase(LAS unsigned char* lds, const Gemm g, const StaticOrder& S, const Epi& E) {
;     ...
;         const bool has_next = S.next(ui + 1, nxt);
;         const char* nA = has_next ? (const char*)g.A + (size_t)nxt.pm * tstepA : cA; const char* nB = has_next ? (const char*)g.Bt + (size_t)nxt.pn * tstepB : cB;
;         for (int t = 0; t < nt; t += 2) {
;             const bool last = (t == nt - 2);
;             const char* a1 = cA + (size_t)(t + 1) * kstep;
;             const char* a2 = last ? nA : cA + (size_t)(t + 2) * kstep; const char* b2 = last ? nB : cB + (size_t)(t + 2) * kstep;
;     ...
; #pragma unroll
;         for (int a = 0; a < 2; ++a)
; #pragma unroll
;             for (int b = 0; b < 2; ++b)
; #pragma unroll
;                 for (int m = 0; m < 4; ++m)
; #pragma unroll
;                     for (int n = 0; n < 2; ++n) acc[a][b][m][n] = (f32x4){0.f, 0.f, 0.f, 0.f};
;         cur = nxt; cA = nA; cB = nB; ++ui;
.LBB0_458:
	s_ashr_i32 s35, s34, 31
	s_lshl_b64 s[36:37], s[34:35], 20
	s_add_u32 s36, s33, s36
	s_addc_u32 s37, s46, s37
	s_and_b64 s[38:39], s[0:1], exec
	s_cselect_b32 s5, s37, s41
	s_cselect_b32 s7, s36, s40
	s_ashr_i32 s31, s30, 31
	s_lshl_b64 s[38:39], s[30:31], 20
	s_add_u32 s38, s47, s38
	s_addc_u32 s39, s48, s39
	s_and_b64 s[42:43], s[0:1], exec
	s_cselect_b32 s10, s39, s9
	s_cselect_b32 s31, s38, s8
	s_add_u32 s35, s8, 0x100
	s_addc_u32 s44, s9, 0
	s_add_u32 s8, s40, 0x80080
	v_mov_b32_e32 v4, 0
	s_addc_u32 s9, s41, 0
	s_mov_b32 s45, -2
	v_mov_b32_e32 v5, v4
	v_mov_b32_e32 v6, v4
	v_mov_b32_e32 v7, v4
	v_mov_b32_e32 v12, v4
	v_mov_b32_e32 v13, v4
	v_mov_b32_e32 v14, v4
	v_mov_b32_e32 v15, v4
	v_mov_b32_e32 v20, v4
	v_mov_b32_e32 v21, v4
	v_mov_b32_e32 v22, v4
	v_mov_b32_e32 v23, v4
	v_mov_b32_e32 v28, v4
	v_mov_b32_e32 v29, v4
	v_mov_b32_e32 v30, v4
	v_mov_b32_e32 v31, v4
	v_mov_b32_e32 v36, v4
	v_mov_b32_e32 v37, v4
	v_mov_b32_e32 v38, v4
	v_mov_b32_e32 v39, v4
	v_mov_b32_e32 v44, v4
	v_mov_b32_e32 v45, v4
	v_mov_b32_e32 v46, v4
	v_mov_b32_e32 v47, v4
	v_mov_b32_e32 v52, v4
	v_mov_b32_e32 v53, v4
	v_mov_b32_e32 v54, v4
	v_mov_b32_e32 v55, v4
	v_mov_b32_e32 v60, v4
	v_mov_b32_e32 v61, v4
	v_mov_b32_e32 v62, v4
	v_mov_b32_e32 v63, v4
	v_mov_b32_e32 v0, v4
	v_mov_b32_e32 v1, v4
	v_mov_b32_e32 v2, v4
	v_mov_b32_e32 v3, v4
	v_mov_b32_e32 v8, v4
	v_mov_b32_e32 v9, v4
	v_mov_b32_e32 v10, v4
	v_mov_b32_e32 v11, v4
	v_mov_b32_e32 v16, v4
	v_mov_b32_e32 v17, v4
	v_mov_b32_e32 v18, v4
	v_mov_b32_e32 v19, v4
	v_mov_b32_e32 v24, v4
	v_mov_b32_e32 v25, v4
	v_mov_b32_e32 v26, v4
	v_mov_b32_e32 v27, v4
	v_mov_b32_e32 v32, v4
	v_mov_b32_e32 v33, v4
	v_mov_b32_e32 v34, v4
	v_mov_b32_e32 v35, v4
	v_mov_b32_e32 v40, v4
	v_mov_b32_e32 v41, v4
	v_mov_b32_e32 v42, v4
	v_mov_b32_e32 v43, v4
	v_mov_b32_e32 v48, v4
	v_mov_b32_e32 v49, v4
	v_mov_b32_e32 v50, v4
	v_mov_b32_e32 v51, v4
	v_mov_b32_e32 v56, v4
	v_mov_b32_e32 v57, v4
	v_mov_b32_e32 v58, v4
	v_mov_b32_e32 v59, v4
	v_mov_b32_e32 v68, v4
	v_mov_b32_e32 v69, v4
	v_mov_b32_e32 v70, v4
	v_mov_b32_e32 v71, v4
	v_mov_b32_e32 v76, v4
	v_mov_b32_e32 v77, v4
	v_mov_b32_e32 v78, v4
	v_mov_b32_e32 v79, v4
	v_mov_b32_e32 v84, v4
	v_mov_b32_e32 v85, v4
	v_mov_b32_e32 v86, v4
	v_mov_b32_e32 v87, v4
	v_mov_b32_e32 v92, v4
	v_mov_b32_e32 v93, v4
	v_mov_b32_e32 v94, v4
	v_mov_b32_e32 v95, v4
	v_mov_b32_e32 v100, v4
	v_mov_b32_e32 v101, v4
	v_mov_b32_e32 v102, v4
	v_mov_b32_e32 v103, v4
	v_mov_b32_e32 v108, v4
	v_mov_b32_e32 v109, v4
	v_mov_b32_e32 v110, v4
	v_mov_b32_e32 v111, v4
	v_mov_b32_e32 v116, v4
	v_mov_b32_e32 v117, v4
	v_mov_b32_e32 v118, v4
	v_mov_b32_e32 v119, v4
	v_mov_b32_e32 v124, v4
	v_mov_b32_e32 v125, v4
	v_mov_b32_e32 v126, v4
	v_mov_b32_e32 v127, v4
	v_mov_b32_e32 v64, v4
	v_mov_b32_e32 v65, v4
	v_mov_b32_e32 v66, v4
	v_mov_b32_e32 v67, v4
	v_mov_b32_e32 v72, v4
	v_mov_b32_e32 v73, v4
	v_mov_b32_e32 v74, v4
	v_mov_b32_e32 v75, v4
	v_mov_b32_e32 v80, v4
	v_mov_b32_e32 v81, v4
	v_mov_b32_e32 v82, v4
	v_mov_b32_e32 v83, v4
	v_mov_b32_e32 v88, v4
	v_mov_b32_e32 v89, v4
	v_mov_b32_e32 v90, v4
	v_mov_b32_e32 v91, v4
	v_mov_b32_e32 v96, v4
	v_mov_b32_e32 v97, v4
	v_mov_b32_e32 v98, v4
	v_mov_b32_e32 v99, v4
	v_mov_b32_e32 v104, v4
	v_mov_b32_e32 v105, v4
	v_mov_b32_e32 v106, v4
	v_mov_b32_e32 v107, v4
	v_mov_b32_e32 v112, v4
	v_mov_b32_e32 v113, v4
	v_mov_b32_e32 v114, v4
	v_mov_b32_e32 v115, v4
	v_mov_b32_e32 v120, v4
	v_mov_b32_e32 v121, v4
	v_mov_b32_e32 v122, v4
	v_mov_b32_e32 v123, v4
	.p2align	6

; template <class Epi, bool ALIGN_EPI>
; __device__ __forceinline__ void gemm_phase(LAS unsigned char* lds, const Gemm g, const StaticOrder& S, const Epi& E) {
;     ...
;         const bool has_next = S.next(ui + 1, nxt);
;         const char* nA = has_next ? (const char*)g.A + (size_t)nxt.pm * tstepA : cA; const char* nB = has_next ? (const char*)g.Bt + (size_t)nxt.pn * tstepB : cB;
;         for (int t = 0; t < nt; t += 2) {
;             const bool last = (t == nt - 2);
;             const char* a1 = cA + (size_t)(t + 1) * kstep;
;             const char* a2 = last ? nA : cA + (size_t)(t + 2) * kstep; const char* b2 = last ? nB : cB + (size_t)(t + 2) * kstep;
;     ...
; #pragma unroll
;         for (int a = 0; a < 2; ++a)
; #pragma unroll
;             for (int b = 0; b < 2; ++b)
; #pragma unroll
;                 for (int m = 0; m < 4; ++m)
; #pragma unroll
;                     for (int n = 0; n < 2; ++n) acc[a][b][m][n] = (f32x4){0.f, 0.f, 0.f, 0.f};
;         cur = nxt; cA = nA; cB = nB; ++ui;
.LBB0_816:
	s_ashr_i32 s15, s14, 31
	s_lshl_b64 s[16:17], s[14:15], 20
	s_add_u32 s16, s29, s16
	s_addc_u32 s17, s30, s17
	s_and_b64 s[18:19], s[0:1], exec
	s_cselect_b32 s15, s17, s25
	s_cselect_b32 s52, s16, s24
	s_ashr_i32 s13, s12, 31
	s_lshl_b64 s[18:19], s[12:13], 19
	s_add_u32 s18, s31, s18
	s_addc_u32 s19, s33, s19
	s_and_b64 s[26:27], s[0:1], exec
	s_cselect_b32 s13, s19, s23
	s_cselect_b32 s53, s18, s22
	s_add_u32 s54, s22, 0x100
	s_addc_u32 s55, s23, 0
	s_add_u32 s22, s24, 0x80080
	v_mov_b32_e32 v0, 0
	s_addc_u32 s23, s25, 0
	s_mov_b32 s56, -2
	v_mov_b32_e32 v1, v0
	v_mov_b32_e32 v2, v0
	v_mov_b32_e32 v3, v0
	v_mov_b32_e32 v4, v0
	v_mov_b32_e32 v5, v0
	v_mov_b32_e32 v6, v0
	v_mov_b32_e32 v7, v0
	v_mov_b32_e32 v16, v0
	v_mov_b32_e32 v17, v0
	v_mov_b32_e32 v18, v0
	v_mov_b32_e32 v19, v0
	v_mov_b32_e32 v20, v0
	v_mov_b32_e32 v21, v0
	v_mov_b32_e32 v22, v0
	v_mov_b32_e32 v23, v0
	v_mov_b32_e32 v32, v0
	v_mov_b32_e32 v33, v0
	v_mov_b32_e32 v34, v0
	v_mov_b32_e32 v35, v0
	v_mov_b32_e32 v36, v0
	v_mov_b32_e32 v37, v0
	v_mov_b32_e32 v38, v0
	v_mov_b32_e32 v39, v0
	v_mov_b32_e32 v48, v0
	v_mov_b32_e32 v49, v0
	v_mov_b32_e32 v50, v0
	v_mov_b32_e32 v51, v0
	v_mov_b32_e32 v52, v0
	v_mov_b32_e32 v53, v0
	v_mov_b32_e32 v54, v0
	v_mov_b32_e32 v55, v0
	v_mov_b32_e32 v8, v0
	v_mov_b32_e32 v9, v0
	v_mov_b32_e32 v10, v0
	v_mov_b32_e32 v11, v0
	v_mov_b32_e32 v12, v0
	v_mov_b32_e32 v13, v0
	v_mov_b32_e32 v14, v0
	v_mov_b32_e32 v15, v0
	v_mov_b32_e32 v24, v0
	v_mov_b32_e32 v25, v0
	v_mov_b32_e32 v26, v0
	v_mov_b32_e32 v27, v0
	v_mov_b32_e32 v28, v0
	v_mov_b32_e32 v29, v0
	v_mov_b32_e32 v30, v0
	v_mov_b32_e32 v31, v0
	v_mov_b32_e32 v40, v0
	v_mov_b32_e32 v41, v0
	v_mov_b32_e32 v42, v0
	v_mov_b32_e32 v43, v0
	v_mov_b32_e32 v44, v0
	v_mov_b32_e32 v45, v0
	v_mov_b32_e32 v46, v0
	v_mov_b32_e32 v47, v0
	v_mov_b32_e32 v56, v0
	v_mov_b32_e32 v57, v0
	v_mov_b32_e32 v58, v0
	v_mov_b32_e32 v59, v0
	v_mov_b32_e32 v60, v0
	v_mov_b32_e32 v61, v0
	v_mov_b32_e32 v62, v0
	v_mov_b32_e32 v63, v0
	v_mov_b32_e32 v64, v0
	v_mov_b32_e32 v65, v0
	v_mov_b32_e32 v66, v0
	v_mov_b32_e32 v67, v0
	v_mov_b32_e32 v68, v0
	v_mov_b32_e32 v69, v0
	v_mov_b32_e32 v70, v0
	v_mov_b32_e32 v71, v0
	v_mov_b32_e32 v80, v0
	v_mov_b32_e32 v81, v0
	v_mov_b32_e32 v82, v0
	v_mov_b32_e32 v83, v0
	v_mov_b32_e32 v84, v0
	v_mov_b32_e32 v85, v0
	v_mov_b32_e32 v86, v0
	v_mov_b32_e32 v87, v0
	v_mov_b32_e32 v96, v0
	v_mov_b32_e32 v97, v0
	v_mov_b32_e32 v98, v0
	v_mov_b32_e32 v99, v0
	v_mov_b32_e32 v100, v0
	v_mov_b32_e32 v101, v0
	v_mov_b32_e32 v102, v0
	v_mov_b32_e32 v103, v0
	v_mov_b32_e32 v112, v0
	v_mov_b32_e32 v113, v0
	v_mov_b32_e32 v114, v0
	v_mov_b32_e32 v115, v0
	v_mov_b32_e32 v116, v0
	v_mov_b32_e32 v117, v0
	v_mov_b32_e32 v118, v0
	v_mov_b32_e32 v119, v0
	v_mov_b32_e32 v72, v0
	v_mov_b32_e32 v73, v0
	v_mov_b32_e32 v74, v0
	v_mov_b32_e32 v75, v0
	v_mov_b32_e32 v76, v0
	v_mov_b32_e32 v77, v0
	v_mov_b32_e32 v78, v0
	v_mov_b32_e32 v79, v0
	v_mov_b32_e32 v88, v0
	v_mov_b32_e32 v89, v0
	v_mov_b32_e32 v90, v0
	v_mov_b32_e32 v91, v0
	v_mov_b32_e32 v92, v0
	v_mov_b32_e32 v93, v0
	v_mov_b32_e32 v94, v0
	v_mov_b32_e32 v95, v0
	v_mov_b32_e32 v104, v0
	v_mov_b32_e32 v105, v0
	v_mov_b32_e32 v106, v0
	v_mov_b32_e32 v107, v0
	v_mov_b32_e32 v108, v0
	v_mov_b32_e32 v109, v0
	v_mov_b32_e32 v110, v0
	v_mov_b32_e32 v111, v0
	v_mov_b32_e32 v120, v0
	v_mov_b32_e32 v121, v0
	v_mov_b32_e32 v122, v0
	v_mov_b32_e32 v123, v0
	v_mov_b32_e32 v124, v0
	v_mov_b32_e32 v125, v0
	v_mov_b32_e32 v126, v0
	v_mov_b32_e32 v127, v0
	.p2align	6

; template <class Epi, bool ALIGN_EPI>
; __device__ __forceinline__ void gemm_phase(LAS unsigned char* lds, const Gemm g, const StaticOrder& S, const Epi& E) {
;     ...
;         const bool has_next = S.next(ui + 1, nxt);
;         const char* nA = has_next ? (const char*)g.A + (size_t)nxt.pm * tstepA : cA; const char* nB = has_next ? (const char*)g.Bt + (size_t)nxt.pn * tstepB : cB;
;         for (int t = 0; t < nt; t += 2) {
;             const bool last = (t == nt - 2);
;             const char* a1 = cA + (size_t)(t + 1) * kstep;
;             const char* a2 = last ? nA : cA + (size_t)(t + 2) * kstep; const char* b2 = last ? nB : cB + (size_t)(t + 2) * kstep;
;     ...
; #pragma unroll
;         for (int a = 0; a < 2; ++a)
; #pragma unroll
;             for (int b = 0; b < 2; ++b)
; #pragma unroll
;                 for (int m = 0; m < 4; ++m)
; #pragma unroll
;                     for (int n = 0; n < 2; ++n) acc[a][b][m][n] = (f32x4){0.f, 0.f, 0.f, 0.f};
;         cur = nxt; cA = nA; cB = nB; ++ui;
.LBB0_1081:
	s_ashr_i32 s27, s26, 31
	s_lshl_b64 s[28:29], s[26:27], 20
	s_add_u32 s28, s2, s28
	s_addc_u32 s29, s33, s29
	s_and_b64 s[30:31], s[6:7], exec
	s_cselect_b32 s5, s29, s39
	s_cselect_b32 s27, s28, s38
	s_ashr_i32 s25, s24, 31
	s_lshl_b64 s[30:31], s[24:25], 20
	s_add_u32 s30, s42, s30
	s_addc_u32 s31, s43, s31
	s_and_b64 s[40:41], s[6:7], exec
	s_cselect_b32 s25, s31, s37
	s_cselect_b32 s35, s30, s36
	s_add_u32 s59, s36, 0x100
	s_addc_u32 s60, s37, 0
	s_add_u32 s36, s38, 0x80080
	v_mov_b32_e32 v0, 0
	s_addc_u32 s37, s39, 0
	s_mov_b32 s61, -2
	s_waitcnt lgkmcnt(0)
	v_mov_b32_e32 v1, v0
	v_mov_b32_e32 v2, v0
	v_mov_b32_e32 v3, v0
	v_mov_b32_e32 v4, v0
	v_mov_b32_e32 v5, v0
	v_mov_b32_e32 v6, v0
	v_mov_b32_e32 v7, v0
	v_mov_b32_e32 v16, v0
	v_mov_b32_e32 v17, v0
	v_mov_b32_e32 v18, v0
	v_mov_b32_e32 v19, v0
	v_mov_b32_e32 v20, v0
	v_mov_b32_e32 v21, v0
	v_mov_b32_e32 v22, v0
	v_mov_b32_e32 v23, v0
	v_mov_b32_e32 v32, v0
	v_mov_b32_e32 v33, v0
	v_mov_b32_e32 v34, v0
	v_mov_b32_e32 v35, v0
	v_mov_b32_e32 v36, v0
	v_mov_b32_e32 v37, v0
	v_mov_b32_e32 v38, v0
	v_mov_b32_e32 v39, v0
	v_mov_b32_e32 v48, v0
	v_mov_b32_e32 v49, v0
	v_mov_b32_e32 v50, v0
	v_mov_b32_e32 v51, v0
	v_mov_b32_e32 v52, v0
	v_mov_b32_e32 v53, v0
	v_mov_b32_e32 v54, v0
	v_mov_b32_e32 v55, v0
	v_mov_b32_e32 v8, v0
	v_mov_b32_e32 v9, v0
	v_mov_b32_e32 v10, v0
	v_mov_b32_e32 v11, v0
	v_mov_b32_e32 v12, v0
	v_mov_b32_e32 v13, v0
	v_mov_b32_e32 v14, v0
	v_mov_b32_e32 v15, v0
	v_mov_b32_e32 v24, v0
	v_mov_b32_e32 v25, v0
	v_mov_b32_e32 v26, v0
	v_mov_b32_e32 v27, v0
	v_mov_b32_e32 v28, v0
	v_mov_b32_e32 v29, v0
	v_mov_b32_e32 v30, v0
	v_mov_b32_e32 v31, v0
	v_mov_b32_e32 v40, v0
	v_mov_b32_e32 v41, v0
	v_mov_b32_e32 v42, v0
	v_mov_b32_e32 v43, v0
	v_mov_b32_e32 v44, v0
	v_mov_b32_e32 v45, v0
	v_mov_b32_e32 v46, v0
	v_mov_b32_e32 v47, v0
	v_mov_b32_e32 v56, v0
	v_mov_b32_e32 v57, v0
	v_mov_b32_e32 v58, v0
	v_mov_b32_e32 v59, v0
	v_mov_b32_e32 v60, v0
	v_mov_b32_e32 v61, v0
	v_mov_b32_e32 v62, v0
	v_mov_b32_e32 v63, v0
	v_mov_b32_e32 v68, v0
	v_mov_b32_e32 v69, v0
	v_mov_b32_e32 v70, v0
	v_mov_b32_e32 v71, v0
	v_mov_b32_e32 v80, v0
	v_mov_b32_e32 v81, v0
	v_mov_b32_e32 v82, v0
	v_mov_b32_e32 v83, v0
	v_mov_b32_e32 v96, v0
	v_mov_b32_e32 v97, v0
	v_mov_b32_e32 v98, v0
	v_mov_b32_e32 v99, v0
	v_mov_b32_e32 v100, v0
	v_mov_b32_e32 v101, v0
	v_mov_b32_e32 v102, v0
	v_mov_b32_e32 v103, v0
	v_mov_b32_e32 v112, v0
	v_mov_b32_e32 v113, v0
	v_mov_b32_e32 v114, v0
	v_mov_b32_e32 v115, v0
	v_mov_b32_e32 v116, v0
	v_mov_b32_e32 v117, v0
	v_mov_b32_e32 v118, v0
	v_mov_b32_e32 v119, v0
	v_mov_b32_e32 v128, v0
	v_mov_b32_e32 v129, v0
	v_mov_b32_e32 v130, v0
	v_mov_b32_e32 v131, v0
	v_mov_b32_e32 v132, v0
	v_mov_b32_e32 v133, v0
	v_mov_b32_e32 v134, v0
	v_mov_b32_e32 v135, v0
	v_mov_b32_e32 v88, v0
	v_mov_b32_e32 v89, v0
	v_mov_b32_e32 v90, v0
	v_mov_b32_e32 v91, v0
	v_mov_b32_e32 v92, v0
	v_mov_b32_e32 v93, v0
	v_mov_b32_e32 v94, v0
	v_mov_b32_e32 v95, v0
	v_mov_b32_e32 v104, v0
	v_mov_b32_e32 v105, v0
	v_mov_b32_e32 v106, v0
	v_mov_b32_e32 v107, v0
	v_mov_b32_e32 v108, v0
	v_mov_b32_e32 v109, v0
	v_mov_b32_e32 v110, v0
	v_mov_b32_e32 v111, v0
	v_mov_b32_e32 v120, v0
	v_mov_b32_e32 v121, v0
	v_mov_b32_e32 v122, v0
	v_mov_b32_e32 v123, v0
	v_mov_b32_e32 v124, v0
	v_mov_b32_e32 v125, v0
	v_mov_b32_e32 v126, v0
	v_mov_b32_e32 v127, v0
	v_mov_b32_e32 v136, v0
	v_mov_b32_e32 v137, v0
	v_mov_b32_e32 v138, v0
	v_mov_b32_e32 v139, v0
	v_mov_b32_e32 v140, v0
	v_mov_b32_e32 v141, v0
	v_mov_b32_e32 v142, v0
	v_mov_b32_e32 v143, v0
	.p2align	6

; template <class Epi, bool ALIGN_EPI>
; __device__ __forceinline__ void gemm_phase(LAS unsigned char* lds, const Gemm g, const StaticOrder& S, const Epi& E) {
;     ...
;         const bool has_next = S.next(ui + 1, nxt);
;         const char* nA = has_next ? (const char*)g.A + (size_t)nxt.pm * tstepA : cA; const char* nB = has_next ? (const char*)g.Bt + (size_t)nxt.pn * tstepB : cB;
;         for (int t = 0; t < nt; t += 2) {
;             const bool last = (t == nt - 2);
;             const char* a1 = cA + (size_t)(t + 1) * kstep;
;             const char* a2 = last ? nA : cA + (size_t)(t + 2) * kstep; const char* b2 = last ? nB : cB + (size_t)(t + 2) * kstep;
;     ...
; #pragma unroll
;         for (int a = 0; a < 2; ++a)
; #pragma unroll
;             for (int b = 0; b < 2; ++b)
; #pragma unroll
;                 for (int m = 0; m < 4; ++m)
; #pragma unroll
;                     for (int n = 0; n < 2; ++n) acc[a][b][m][n] = (f32x4){0.f, 0.f, 0.f, 0.f};
;         cur = nxt; cA = nA; cB = nB; ++ui;
.LBB0_1292:
	s_ashr_i32 s19, s18, 31
	s_lshl_b64 s[20:21], s[18:19], 20
	s_add_u32 s20, s30, s20
	s_addc_u32 s21, s31, s21
	s_and_b64 s[22:23], s[0:1], exec
	s_cselect_b32 s19, s21, s27
	s_cselect_b32 s52, s20, s26
	s_ashr_i32 s17, s16, 31
	s_lshl_b64 s[22:23], s[16:17], 20
	s_add_u32 s22, s33, s22
	s_addc_u32 s23, s34, s23
	s_and_b64 s[28:29], s[0:1], exec
	s_cselect_b32 s17, s23, s25
	s_cselect_b32 s53, s22, s24
	s_add_u32 s54, s24, 0x100
	s_addc_u32 s55, s25, 0
	s_add_u32 s24, s26, 0x80080
	v_mov_b32_e32 v0, 0
	s_addc_u32 s25, s27, 0
	s_mov_b32 s56, -2
	v_mov_b32_e32 v1, v0
	v_mov_b32_e32 v2, v0
	v_mov_b32_e32 v3, v0
	v_mov_b32_e32 v4, v0
	v_mov_b32_e32 v5, v0
	v_mov_b32_e32 v6, v0
	v_mov_b32_e32 v7, v0
	v_mov_b32_e32 v16, v0
	v_mov_b32_e32 v17, v0
	v_mov_b32_e32 v18, v0
	v_mov_b32_e32 v19, v0
	v_mov_b32_e32 v20, v0
	v_mov_b32_e32 v21, v0
	v_mov_b32_e32 v22, v0
	v_mov_b32_e32 v23, v0
	v_mov_b32_e32 v32, v0
	v_mov_b32_e32 v33, v0
	v_mov_b32_e32 v34, v0
	v_mov_b32_e32 v35, v0
	v_mov_b32_e32 v36, v0
	v_mov_b32_e32 v37, v0
	v_mov_b32_e32 v38, v0
	v_mov_b32_e32 v39, v0
	v_mov_b32_e32 v48, v0
	v_mov_b32_e32 v49, v0
	v_mov_b32_e32 v50, v0
	v_mov_b32_e32 v51, v0
	v_mov_b32_e32 v52, v0
	v_mov_b32_e32 v53, v0
	v_mov_b32_e32 v54, v0
	v_mov_b32_e32 v55, v0
	v_mov_b32_e32 v8, v0
	v_mov_b32_e32 v9, v0
	v_mov_b32_e32 v10, v0
	v_mov_b32_e32 v11, v0
	v_mov_b32_e32 v12, v0
	v_mov_b32_e32 v13, v0
	v_mov_b32_e32 v14, v0
	v_mov_b32_e32 v15, v0
	v_mov_b32_e32 v24, v0
	v_mov_b32_e32 v25, v0
	v_mov_b32_e32 v26, v0
	v_mov_b32_e32 v27, v0
	v_mov_b32_e32 v28, v0
	v_mov_b32_e32 v29, v0
	v_mov_b32_e32 v30, v0
	v_mov_b32_e32 v31, v0
	v_mov_b32_e32 v40, v0
	v_mov_b32_e32 v41, v0
	v_mov_b32_e32 v42, v0
	v_mov_b32_e32 v43, v0
	v_mov_b32_e32 v44, v0
	v_mov_b32_e32 v45, v0
	v_mov_b32_e32 v46, v0
	v_mov_b32_e32 v47, v0
	v_mov_b32_e32 v56, v0
	v_mov_b32_e32 v57, v0
	v_mov_b32_e32 v58, v0
	v_mov_b32_e32 v59, v0
	v_mov_b32_e32 v60, v0
	v_mov_b32_e32 v61, v0
	v_mov_b32_e32 v62, v0
	v_mov_b32_e32 v63, v0
	v_mov_b32_e32 v64, v0
	v_mov_b32_e32 v65, v0
	v_mov_b32_e32 v66, v0
	v_mov_b32_e32 v67, v0
	v_mov_b32_e32 v68, v0
	v_mov_b32_e32 v69, v0
	v_mov_b32_e32 v70, v0
	v_mov_b32_e32 v71, v0
	v_mov_b32_e32 v80, v0
	v_mov_b32_e32 v81, v0
	v_mov_b32_e32 v82, v0
	v_mov_b32_e32 v83, v0
	v_mov_b32_e32 v84, v0
	v_mov_b32_e32 v85, v0
	v_mov_b32_e32 v86, v0
	v_mov_b32_e32 v87, v0
	v_mov_b32_e32 v96, v0
	v_mov_b32_e32 v97, v0
	v_mov_b32_e32 v98, v0
	v_mov_b32_e32 v99, v0
	v_mov_b32_e32 v100, v0
	v_mov_b32_e32 v101, v0
	v_mov_b32_e32 v102, v0
	v_mov_b32_e32 v103, v0
	v_mov_b32_e32 v112, v0
	v_mov_b32_e32 v113, v0
	v_mov_b32_e32 v114, v0
	v_mov_b32_e32 v115, v0
	v_mov_b32_e32 v116, v0
	v_mov_b32_e32 v117, v0
	v_mov_b32_e32 v118, v0
	v_mov_b32_e32 v119, v0
	v_mov_b32_e32 v72, v0
	v_mov_b32_e32 v73, v0
	v_mov_b32_e32 v74, v0
	v_mov_b32_e32 v75, v0
	v_mov_b32_e32 v76, v0
	v_mov_b32_e32 v77, v0
	v_mov_b32_e32 v78, v0
	v_mov_b32_e32 v79, v0
	v_mov_b32_e32 v88, v0
	v_mov_b32_e32 v89, v0
	v_mov_b32_e32 v90, v0
	v_mov_b32_e32 v91, v0
	v_mov_b32_e32 v92, v0
	v_mov_b32_e32 v93, v0
	v_mov_b32_e32 v94, v0
	v_mov_b32_e32 v95, v0
	v_mov_b32_e32 v104, v0
	v_mov_b32_e32 v105, v0
	v_mov_b32_e32 v106, v0
	v_mov_b32_e32 v107, v0
	v_mov_b32_e32 v108, v0
	v_mov_b32_e32 v109, v0
	v_mov_b32_e32 v110, v0
	v_mov_b32_e32 v111, v0
	v_mov_b32_e32 v120, v0
	v_mov_b32_e32 v121, v0
	v_mov_b32_e32 v122, v0
	v_mov_b32_e32 v123, v0
	v_mov_b32_e32 v124, v0
	v_mov_b32_e32 v125, v0
	v_mov_b32_e32 v126, v0
	v_mov_b32_e32 v127, v0
	.p2align	6

; template <class Epi, bool ALIGN_EPI>
; __device__ __forceinline__ void gemm_phase(LAS unsigned char* lds, const Gemm g, const StaticOrder& S, const Epi& E) {
;     ...
; #pragma unroll
;         for (int a = 0; a < 2; ++a)
; #pragma unroll
;             for (int b = 0; b < 2; ++b)
; #pragma unroll
;                 for (int m = 0; m < 4; ++m)
; #pragma unroll
;                     for (int n = 0; n < 2; ++n) acc[a][b][m][n] = (f32x4){0.f, 0.f, 0.f, 0.f};
;         cur = nxt; cA = nA; cB = nB; ++ui;
.LBB0_1378:
	s_add_u32 s55, s26, 0x100
	v_mov_b32_e32 v0, 0
	s_addc_u32 s56, s27, 0
	s_mov_b32 s57, -2
	s_waitcnt lgkmcnt(0)
	v_mov_b32_e32 v1, v0
	v_mov_b32_e32 v2, v0
	v_mov_b32_e32 v3, v0
	v_mov_b32_e32 v4, v0
	v_mov_b32_e32 v5, v0
	v_mov_b32_e32 v6, v0
	v_mov_b32_e32 v7, v0
	v_mov_b32_e32 v16, v0
	v_mov_b32_e32 v17, v0
	v_mov_b32_e32 v18, v0
	v_mov_b32_e32 v19, v0
	v_mov_b32_e32 v20, v0
	v_mov_b32_e32 v21, v0
	v_mov_b32_e32 v22, v0
	v_mov_b32_e32 v23, v0
	v_mov_b32_e32 v32, v0
	v_mov_b32_e32 v33, v0
	v_mov_b32_e32 v34, v0
	v_mov_b32_e32 v35, v0
	v_mov_b32_e32 v36, v0
	v_mov_b32_e32 v37, v0
	v_mov_b32_e32 v38, v0
	v_mov_b32_e32 v39, v0
	v_mov_b32_e32 v48, v0
	v_mov_b32_e32 v49, v0
	v_mov_b32_e32 v50, v0
	v_mov_b32_e32 v51, v0
	v_mov_b32_e32 v52, v0
	v_mov_b32_e32 v53, v0
	v_mov_b32_e32 v54, v0
	v_mov_b32_e32 v55, v0
	v_mov_b32_e32 v8, v0
	v_mov_b32_e32 v9, v0
	v_mov_b32_e32 v10, v0
	v_mov_b32_e32 v11, v0
	v_mov_b32_e32 v12, v0
	v_mov_b32_e32 v13, v0
	v_mov_b32_e32 v14, v0
	v_mov_b32_e32 v15, v0
	v_mov_b32_e32 v24, v0
	v_mov_b32_e32 v25, v0
	v_mov_b32_e32 v26, v0
	v_mov_b32_e32 v27, v0
	v_mov_b32_e32 v28, v0
	v_mov_b32_e32 v29, v0
	v_mov_b32_e32 v30, v0
	v_mov_b32_e32 v31, v0
	v_mov_b32_e32 v40, v0
	v_mov_b32_e32 v41, v0
	v_mov_b32_e32 v42, v0
	v_mov_b32_e32 v43, v0
	v_mov_b32_e32 v44, v0
	v_mov_b32_e32 v45, v0
	v_mov_b32_e32 v46, v0
	v_mov_b32_e32 v47, v0
	v_mov_b32_e32 v56, v0
	v_mov_b32_e32 v57, v0
	v_mov_b32_e32 v58, v0
	v_mov_b32_e32 v59, v0
	v_mov_b32_e32 v60, v0
	v_mov_b32_e32 v61, v0
	v_mov_b32_e32 v62, v0
	v_mov_b32_e32 v63, v0
	v_mov_b32_e32 v64, v0
	v_mov_b32_e32 v65, v0
	v_mov_b32_e32 v66, v0
	v_mov_b32_e32 v67, v0
	v_mov_b32_e32 v68, v0
	v_mov_b32_e32 v69, v0
	v_mov_b32_e32 v70, v0
	v_mov_b32_e32 v71, v0
	v_mov_b32_e32 v92, v0
	v_mov_b32_e32 v93, v0
	v_mov_b32_e32 v94, v0
	v_mov_b32_e32 v95, v0
	v_mov_b32_e32 v100, v0
	v_mov_b32_e32 v101, v0
	v_mov_b32_e32 v102, v0
	v_mov_b32_e32 v103, v0
	v_mov_b32_e32 v112, v0
	v_mov_b32_e32 v113, v0
	v_mov_b32_e32 v114, v0
	v_mov_b32_e32 v115, v0
	v_mov_b32_e32 v116, v0
	v_mov_b32_e32 v117, v0
	v_mov_b32_e32 v118, v0
	v_mov_b32_e32 v119, v0
	v_mov_b32_e32 v128, v0
	v_mov_b32_e32 v129, v0
	v_mov_b32_e32 v130, v0
	v_mov_b32_e32 v131, v0
	v_mov_b32_e32 v132, v0
	v_mov_b32_e32 v133, v0
	v_mov_b32_e32 v134, v0
	v_mov_b32_e32 v135, v0
	v_mov_b32_e32 v76, v0
	v_mov_b32_e32 v77, v0
	v_mov_b32_e32 v78, v0
	v_mov_b32_e32 v79, v0
	v_mov_b32_e32 v80, v0
	v_mov_b32_e32 v81, v0
	v_mov_b32_e32 v82, v0
	v_mov_b32_e32 v83, v0
	v_mov_b32_e32 v104, v0
	v_mov_b32_e32 v105, v0
	v_mov_b32_e32 v106, v0
	v_mov_b32_e32 v107, v0
	v_mov_b32_e32 v108, v0
	v_mov_b32_e32 v109, v0
	v_mov_b32_e32 v110, v0
	v_mov_b32_e32 v111, v0
	v_mov_b32_e32 v120, v0
	v_mov_b32_e32 v121, v0
	v_mov_b32_e32 v122, v0
	v_mov_b32_e32 v123, v0
	v_mov_b32_e32 v124, v0
	v_mov_b32_e32 v125, v0
	v_mov_b32_e32 v126, v0
	v_mov_b32_e32 v127, v0
	v_mov_b32_e32 v136, v0
	v_mov_b32_e32 v137, v0
	v_mov_b32_e32 v138, v0
	v_mov_b32_e32 v139, v0
	v_mov_b32_e32 v140, v0
	v_mov_b32_e32 v141, v0
	v_mov_b32_e32 v142, v0
	v_mov_b32_e32 v143, v0
	.p2align	6
